# residual epilogue: gate-staging wait and barrier sunk below the 16 residual loads (vmcnt(16)), to the first read of the staged gate vectors
# speedup vs baseline: 1.0091x; 1.0063x over previous
; #define LAS __attribute__((address_space(3)))
; __device__ __forceinline__ unsigned cvt_pk_bf16(float lo, float hi) { const cvt_f32x2_t v = {lo, hi}; const cvt_bf16x2_t b = __builtin_convertvector(v, cvt_bf16x2_t); return __builtin_bit_cast(unsigned, b); }
;     __device__ __forceinline__ void operator()(const f32x4 (&acc)[2][2][4][2], const Unit& u, int wr, int wc, int fr, int fq) const {
;     ...
;         { const int t = (wr * 4 + wc) * 64 + fq * 16 + fr;
;           if (t < 64) ((LAS f32x4*)gl)[t] = *(const f32x4*)(gate + (size_t)b * gate_ld + u.pn * 256 + 4 * t);
;           else if (t < 128 && gmn) ((LAS f32x4*)gl)[t] = *(const f32x4*)(gmn + (size_t)b * DM + u.pn * 256 + 4 * (t - 64));
;           asm volatile("s_waitcnt vmcnt(0) lgkmcnt(0)" ::: "memory"); __builtin_amdgcn_s_barrier(); asm volatile("" ::: "memory"); }
;         const LAS float* gtp = gl + wc * 32 + 8 * fq; const LAS float* gmp = gl + 256 + wc * 32 + 8 * fq;
; #pragma unroll
;         for (int ai = 0; ai < 2; ++ai) {
;             f32x4 xr[4][2][2];
; #pragma unroll
;             for (int m = 0; m < 4; ++m) { const size_t off = (size_t)(u.pm * 256 + ai * 128 + wr * 64 + m * 16 + fr) * DM + col0;
; #pragma unroll
;                 for (int bj = 0; bj < 2; ++bj)
; #pragma unroll
;                     for (int n = 0; n < 2; ++n) xr[m][bj][n] = *(const f32x4*)(xin + off + 128 * bj + 4 * n); }
;             asm volatile("" ::: "memory");
; #pragma unroll
;             for (int m = 0; m < 4; ++m) {
;                 const int row = u.pm * 256 + ai * 128 + wr * 64 + m * 16 + fr;
;                 const size_t off = (size_t)row * DM + col0;
;                 float ss = 0.f;
; #pragma unroll
;                 for (int bj = 0; bj < 2; ++bj) {
;                     const f32x4 xo0 = xr[m][bj][0] + *(const LAS f32x4*)(gtp + 128 * bj) * acc[ai][bj][m][0], xo1 = xr[m][bj][1] + *(const LAS f32x4*)(gtp + 128 * bj + 4) * acc[ai][bj][m][1];
;                     *(f32x4*)(xout + off + 128 * bj) = xo0; *(f32x4*)(xout + off + 128 * bj + 4) = xo1;
;                     if (gmn) { ss += sq4(xo0) + sq4(xo1); const f32x4 a = xo0 * *(const LAS f32x4*)(gmp + 128 * bj), c = xo1 * *(const LAS f32x4*)(gmp + 128 * bj + 4);
;                         u32x4 w; w.x = cvt_pk_bf16(a[0], a[1]); w.y = cvt_pk_bf16(a[2], a[3]); w.z = cvt_pk_bf16(c[0], c[1]); w.w = cvt_pk_bf16(c[2], c[3]); *(u32x4*)(AX + off + 128 * bj) = w; }
.LBB0_216:
	s_or_b64 exec, exec, s[46:47]
	s_or_b32 s44, s44, s58
	v_lshl_add_u32 v224, v250, 3, s44
	s_lshl_b32 s44, s77, 8
	s_add_i32 s44, s44, s7
	v_add_u32_e32 v226, s44, v106
	v_readlane_b32 s44, v255, 46
	v_lshlrev_b32_e32 v104, 5, v250
	v_ashrrev_i32_e32 v225, 31, v224
	v_readlane_b32 s45, v255, 47
	v_ashrrev_i32_e32 v227, 31, v226
	v_add_u32_e32 v249, s87, v104
	v_add_u32_e32 v192, s8, v104
	v_lshl_add_u64 v[228:229], v[224:225], 2, s[44:45]
	v_lshlrev_b64 v[104:105], 12, v[226:227]
	v_add_u32_e32 v234, 16, v226
	v_lshl_add_u64 v[104:105], v[228:229], 0, v[104:105]
	v_ashrrev_i32_e32 v235, 31, v234
	global_load_dwordx4 v[194:197], v[104:105], off offset:16
	global_load_dwordx4 v[198:201], v[104:105], off
	global_load_dwordx4 v[184:187], v[104:105], off offset:528
	global_load_dwordx4 v[188:191], v[104:105], off offset:512
	v_lshlrev_b64 v[104:105], 12, v[234:235]
	v_add_u32_e32 v232, 32, v226
	v_lshl_add_u64 v[104:105], v[228:229], 0, v[104:105]
	v_ashrrev_i32_e32 v233, 31, v232
	global_load_dwordx4 v[176:179], v[104:105], off offset:16
	global_load_dwordx4 v[180:183], v[104:105], off
	global_load_dwordx4 v[168:171], v[104:105], off offset:528
	global_load_dwordx4 v[172:175], v[104:105], off offset:512
	v_lshlrev_b64 v[104:105], 12, v[232:233]
	v_add_u32_e32 v230, 48, v226
	v_lshl_add_u64 v[104:105], v[228:229], 0, v[104:105]
	v_ashrrev_i32_e32 v231, 31, v230
	global_load_dwordx4 v[160:163], v[104:105], off offset:16
	global_load_dwordx4 v[164:167], v[104:105], off
	global_load_dwordx4 v[152:155], v[104:105], off offset:528
	global_load_dwordx4 v[156:159], v[104:105], off offset:512
	v_lshlrev_b64 v[104:105], 12, v[230:231]
	v_lshl_add_u64 v[112:113], v[228:229], 0, v[104:105]
	global_load_dwordx4 v[136:139], v[112:113], off offset:16
	global_load_dwordx4 v[144:147], v[112:113], off
	global_load_dwordx4 v[104:107], v[112:113], off offset:528
	s_nop 0
	global_load_dwordx4 v[112:115], v[112:113], off offset:512
	v_lshlrev_b64 v[140:141], 10, v[226:227]
	v_lshl_add_u64 v[202:203], v[140:141], 0, v[224:225]
	s_waitcnt vmcnt(16) lgkmcnt(0)
	s_barrier
	ds_read_b128 v[148:151], v249
	ds_read_b128 v[140:143], v249 offset:16
	v_lshl_add_u64 v[236:237], v[202:203], 2, s[20:21]
	v_lshl_add_u32 v236, v202, 2, v246
	v_mov_b32_e32 v251, 0
	s_andn2_b64 vcc, exec, s[40:41]
	v_lshl_add_u64 v[238:239], v[202:203], 1, s[16:17]
	v_lshl_add_u64 v[238:239], v[204:205], 0, v[238:239]
	s_waitcnt vmcnt(0) lgkmcnt(0)
	v_pk_fma_f32 v[128:129], v[128:129], v[140:141], v[194:195]
	v_cndmask_b32_e64 v194, 0, 1, s[40:41]
	v_pk_fma_f32 v[134:135], v[134:135], v[150:151], v[200:201]
	v_pk_fma_f32 v[132:133], v[132:133], v[148:149], v[198:199]
	v_pk_fma_f32 v[130:131], v[130:131], v[142:143], v[196:197]
	v_cmp_ne_u32_e64 s[46:47], 1, v194
	ds_write_b128 v208, v[132:135]
	ds_write_b128 v208, v[128:131] offset:16
	ds_read_b128 v[216:219], v210
	ds_read_b128 v[220:223], v210 offset:1152
	s_waitcnt lgkmcnt(0)
	global_store_dwordx4 v236, v[216:219], s[20:21]
	global_store_dwordx4 v236, v[220:223], s[100:101]
	s_cbranch_vccnz .LBB0_218
	v_mov_b32_e32 v196, v133
	v_mov_b32_e32 v197, v129
	v_mov_b32_e32 v194, v132
	v_mov_b32_e32 v195, v128
	v_pk_mul_f32 v[196:197], v[196:197], v[196:197]
	v_mov_b32_e32 v198, v135
	v_mov_b32_e32 v199, v131
	v_pk_fma_f32 v[194:195], v[194:195], v[194:195], v[196:197]
	v_mov_b32_e32 v196, v134
	v_mov_b32_e32 v197, v130
	v_pk_mul_f32 v[198:199], v[198:199], v[198:199]
	s_nop 0
	v_pk_fma_f32 v[196:197], v[196:197], v[196:197], v[198:199]
	s_nop 0
	v_pk_add_f32 v[194:195], v[194:195], v[196:197]
	s_nop 0
	v_add_f32_e32 v251, v194, v195
	ds_read_b128 v[194:197], v192
	ds_read_b128 v[198:201], v192 offset:16
	s_waitcnt lgkmcnt(1)
	v_pk_mul_f32 v[134:135], v[134:135], v[196:197]
	v_pk_mul_f32 v[132:133], v[132:133], v[194:195]
	s_waitcnt lgkmcnt(0)
	v_pk_mul_f32 v[194:195], v[130:131], v[200:201]
	v_pk_mul_f32 v[130:131], v[128:129], v[198:199]
	v_cvt_pk_bf16_f32 v128, v132, v133
	v_cvt_pk_bf16_f32 v129, v134, v135
	v_cvt_pk_bf16_f32 v130, v130, v131
	v_cvt_pk_bf16_f32 v131, v194, v195
	ds_bpermute_b32 v128, v206, v128
	ds_bpermute_b32 v129, v206, v129
	ds_bpermute_b32 v130, v206, v130
	ds_bpermute_b32 v131, v206, v131
	s_waitcnt lgkmcnt(0)
	global_store_dwordx4 v[238:239], v[128:131], off

; #define LAS __attribute__((address_space(3)))
; __device__ __forceinline__ unsigned cvt_pk_bf16(float lo, float hi) { const cvt_f32x2_t v = {lo, hi}; const cvt_bf16x2_t b = __builtin_convertvector(v, cvt_bf16x2_t); return __builtin_bit_cast(unsigned, b); }
;     __device__ __forceinline__ void operator()(const f32x4 (&acc)[2][2][4][2], const Unit& u, int wr, int wc, int fr, int fq) const {
;     ...
;         { const int t = (wr * 4 + wc) * 64 + fq * 16 + fr;
;           if (t < 64) ((LAS f32x4*)gl)[t] = *(const f32x4*)(gate + (size_t)b * gate_ld + u.pn * 256 + 4 * t);
;           else if (t < 128 && gmn) ((LAS f32x4*)gl)[t] = *(const f32x4*)(gmn + (size_t)b * DM + u.pn * 256 + 4 * (t - 64));
;           asm volatile("s_waitcnt vmcnt(0) lgkmcnt(0)" ::: "memory"); __builtin_amdgcn_s_barrier(); asm volatile("" ::: "memory"); }
;         const LAS float* gtp = gl + wc * 32 + 8 * fq; const LAS float* gmp = gl + 256 + wc * 32 + 8 * fq;
; #pragma unroll
;         for (int ai = 0; ai < 2; ++ai) {
;             f32x4 xr[4][2][2];
; #pragma unroll
;             for (int m = 0; m < 4; ++m) { const size_t off = (size_t)(u.pm * 256 + ai * 128 + wr * 64 + m * 16 + fr) * DM + col0;
; #pragma unroll
;                 for (int bj = 0; bj < 2; ++bj)
; #pragma unroll
;                     for (int n = 0; n < 2; ++n) xr[m][bj][n] = *(const f32x4*)(xin + off + 128 * bj + 4 * n); }
;             asm volatile("" ::: "memory");
; #pragma unroll
;             for (int m = 0; m < 4; ++m) {
;                 const int row = u.pm * 256 + ai * 128 + wr * 64 + m * 16 + fr;
;                 const size_t off = (size_t)row * DM + col0;
;                 float ss = 0.f;
; #pragma unroll
;                 for (int bj = 0; bj < 2; ++bj) {
;                     const f32x4 xo0 = xr[m][bj][0] + *(const LAS f32x4*)(gtp + 128 * bj) * acc[ai][bj][m][0], xo1 = xr[m][bj][1] + *(const LAS f32x4*)(gtp + 128 * bj + 4) * acc[ai][bj][m][1];
;                     *(f32x4*)(xout + off + 128 * bj) = xo0; *(f32x4*)(xout + off + 128 * bj + 4) = xo1;
;                     if (gmn) { ss += sq4(xo0) + sq4(xo1); const f32x4 a = xo0 * *(const LAS f32x4*)(gmp + 128 * bj), c = xo1 * *(const LAS f32x4*)(gmp + 128 * bj + 4);
;                         u32x4 w; w.x = cvt_pk_bf16(a[0], a[1]); w.y = cvt_pk_bf16(a[2], a[3]); w.z = cvt_pk_bf16(c[0], c[1]); w.w = cvt_pk_bf16(c[2], c[3]); *(u32x4*)(AX + off + 128 * bj) = w; }
.LBB0_323:
	s_or_b64 exec, exec, s[46:47]
	s_or_b32 s44, s44, s9
	v_lshl_add_u32 v224, v250, 3, s44
	s_lshl_b32 s44, s77, 8
	s_add_i32 s44, s44, s8
	v_add_u32_e32 v226, s44, v106
	v_readlane_b32 s44, v255, 48
	v_lshlrev_b32_e32 v104, 5, v250
	v_ashrrev_i32_e32 v225, 31, v224
	v_readlane_b32 s45, v255, 49
	v_ashrrev_i32_e32 v227, 31, v226
	v_add_u32_e32 v249, s41, v104
	v_add_u32_e32 v192, s4, v104
	v_lshl_add_u64 v[228:229], v[224:225], 2, s[44:45]
	v_lshlrev_b64 v[104:105], 12, v[226:227]
	v_add_u32_e32 v234, 16, v226
	v_lshl_add_u64 v[104:105], v[228:229], 0, v[104:105]
	v_ashrrev_i32_e32 v235, 31, v234
	global_load_dwordx4 v[194:197], v[104:105], off offset:16
	global_load_dwordx4 v[198:201], v[104:105], off
	global_load_dwordx4 v[184:187], v[104:105], off offset:528
	global_load_dwordx4 v[188:191], v[104:105], off offset:512
	v_lshlrev_b64 v[104:105], 12, v[234:235]
	v_add_u32_e32 v232, 32, v226
	v_lshl_add_u64 v[104:105], v[228:229], 0, v[104:105]
	v_ashrrev_i32_e32 v233, 31, v232
	global_load_dwordx4 v[176:179], v[104:105], off offset:16
	global_load_dwordx4 v[180:183], v[104:105], off
	global_load_dwordx4 v[168:171], v[104:105], off offset:528
	global_load_dwordx4 v[172:175], v[104:105], off offset:512
	v_lshlrev_b64 v[104:105], 12, v[232:233]
	v_add_u32_e32 v230, 48, v226
	v_lshl_add_u64 v[104:105], v[228:229], 0, v[104:105]
	v_ashrrev_i32_e32 v231, 31, v230
	global_load_dwordx4 v[160:163], v[104:105], off offset:16
	global_load_dwordx4 v[164:167], v[104:105], off
	global_load_dwordx4 v[152:155], v[104:105], off offset:528
	global_load_dwordx4 v[156:159], v[104:105], off offset:512
	v_lshlrev_b64 v[104:105], 12, v[230:231]
	v_lshl_add_u64 v[112:113], v[228:229], 0, v[104:105]
	global_load_dwordx4 v[136:139], v[112:113], off offset:16
	global_load_dwordx4 v[144:147], v[112:113], off
	global_load_dwordx4 v[104:107], v[112:113], off offset:528
	s_nop 0
	global_load_dwordx4 v[112:115], v[112:113], off offset:512
	v_lshlrev_b64 v[140:141], 10, v[226:227]
	v_lshl_add_u64 v[202:203], v[140:141], 0, v[224:225]
	s_waitcnt vmcnt(16) lgkmcnt(0)
	s_barrier
	ds_read_b128 v[148:151], v249
	ds_read_b128 v[140:143], v249 offset:16
	v_lshl_add_u64 v[236:237], v[202:203], 2, s[6:7]
	v_lshl_add_u32 v236, v202, 2, v246
	v_mov_b32_e32 v251, 0
	s_andn2_b64 vcc, exec, s[38:39]
	v_lshl_add_u64 v[238:239], v[202:203], 1, s[16:17]
	v_lshl_add_u64 v[238:239], v[204:205], 0, v[238:239]
	s_waitcnt vmcnt(0) lgkmcnt(0)
	v_pk_fma_f32 v[128:129], v[128:129], v[140:141], v[194:195]
	v_cndmask_b32_e64 v194, 0, 1, s[38:39]
	v_pk_fma_f32 v[134:135], v[134:135], v[150:151], v[200:201]
	v_pk_fma_f32 v[132:133], v[132:133], v[148:149], v[198:199]
	v_pk_fma_f32 v[130:131], v[130:131], v[142:143], v[196:197]
	v_cmp_ne_u32_e64 s[46:47], 1, v194
	ds_write_b128 v208, v[132:135]
	ds_write_b128 v208, v[128:131] offset:16
	ds_read_b128 v[216:219], v210
	ds_read_b128 v[220:223], v210 offset:1152
	s_waitcnt lgkmcnt(0)
	global_store_dwordx4 v236, v[216:219], s[6:7]
	global_store_dwordx4 v236, v[220:223], s[100:101]
	s_cbranch_vccnz .LBB0_325
	v_mov_b32_e32 v196, v133
	v_mov_b32_e32 v197, v129
	v_mov_b32_e32 v194, v132
	v_mov_b32_e32 v195, v128
	v_pk_mul_f32 v[196:197], v[196:197], v[196:197]
	v_mov_b32_e32 v198, v135
	v_mov_b32_e32 v199, v131
	v_pk_fma_f32 v[194:195], v[194:195], v[194:195], v[196:197]
	v_mov_b32_e32 v196, v134
	v_mov_b32_e32 v197, v130
	v_pk_mul_f32 v[198:199], v[198:199], v[198:199]
	s_nop 0
	v_pk_fma_f32 v[196:197], v[196:197], v[196:197], v[198:199]
	s_nop 0
	v_pk_add_f32 v[194:195], v[194:195], v[196:197]
	s_nop 0
	v_add_f32_e32 v251, v194, v195
	ds_read_b128 v[194:197], v192
	ds_read_b128 v[198:201], v192 offset:16
	s_waitcnt lgkmcnt(1)
	v_pk_mul_f32 v[134:135], v[134:135], v[196:197]
	v_pk_mul_f32 v[132:133], v[132:133], v[194:195]
	s_waitcnt lgkmcnt(0)
	v_pk_mul_f32 v[194:195], v[130:131], v[200:201]
	v_pk_mul_f32 v[130:131], v[128:129], v[198:199]
	v_cvt_pk_bf16_f32 v128, v132, v133
	v_cvt_pk_bf16_f32 v129, v134, v135
	v_cvt_pk_bf16_f32 v130, v130, v131
	v_cvt_pk_bf16_f32 v131, v194, v195
	ds_bpermute_b32 v128, v206, v128
	ds_bpermute_b32 v129, v206, v129
	ds_bpermute_b32 v130, v206, v130
	ds_bpermute_b32 v131, v206, v131
	s_waitcnt lgkmcnt(0)
	global_store_dwordx4 v[238:239], v[128:131], off
